# nt cache policy on the once-read f32 weight loads of the conversion phases (w_ada, w_in, w_kv, w_br, w_out, w_ff)
# speedup vs baseline: 1.0062x; 1.0062x over previous
.LBB0_51:
	v_lshl_add_u64 v[62:63], v[58:59], 0, v[56:57]
	ds_read2_b32 v[60:61], v87 offset1:42
	v_add_u32_e32 v93, 0x10000, v87
	v_lshl_add_u64 v[66:67], v[58:59], 0, v[54:55]
	v_lshl_add_u64 v[68:69], v[58:59], 0, v[52:53]
	ds_read2_b32 v[64:65], v87 offset0:84 offset1:126
	ds_read2_b32 v[70:71], v87 offset0:168 offset1:210
	ds_read_b32 v110, v87 offset:25584
	ds_read_b32 v112, v87 offset:1008
	ds_read_b32 v114, v87 offset:9200
	ds_read_b32 v116, v87 offset:17392
	ds_read_b32 v118, v87 offset:33776
	ds_read_b32 v120, v87 offset:41968
	ds_read_b32 v122, v87 offset:58352
	ds_read_b32 v124, v87 offset:50160
	global_load_dwordx4 v[94:97], v[62:63], off nt
	global_load_dwordx4 v[98:101], v[66:67], off nt
	v_add_u32_e32 v88, 0x2000, v87
	v_add_u32_e32 v89, 0x4000, v87
	v_add_u32_e32 v90, 0x6000, v87
	v_add_u32_e32 v91, 0x8000, v87
	v_add_u32_e32 v92, 0xa000, v87
	v_add_u32_e32 v111, 0xc000, v87
	v_add_u32_e32 v113, 0xe000, v87
	ds_read_b32 v62, v93
	ds_read2_b32 v[126:127], v88 offset1:42
	ds_read2_b32 v[128:129], v89 offset1:42
	ds_read2_b32 v[130:131], v90 offset1:42
	ds_read2_b32 v[132:133], v91 offset1:42
	ds_read2_b32 v[134:135], v92 offset1:42
	ds_read2_b32 v[136:137], v111 offset1:42
	ds_read2_b32 v[138:139], v113 offset1:42
	global_load_dwordx4 v[66:69], v[68:69], off nt
	v_add_u32_e32 v102, 0x100a8, v87
	v_add_u32_e32 v103, 0x10150, v87
	v_lshl_add_u64 v[72:73], v[58:59], 0, v[50:51]
	v_lshl_add_u64 v[74:75], v[58:59], 0, v[48:49]
	ds_read_b32 v140, v102
	ds_read_b32 v142, v103
	ds_read2_b32 v[144:145], v88 offset0:84 offset1:126
	ds_read2_b32 v[146:147], v89 offset0:84 offset1:126
	ds_read2_b32 v[148:149], v90 offset0:84 offset1:126
	ds_read2_b32 v[150:151], v91 offset0:84 offset1:126
	ds_read2_b32 v[152:153], v92 offset0:84 offset1:126
	ds_read2_b32 v[154:155], v111 offset0:84 offset1:126
	ds_read2_b32 v[156:157], v113 offset0:84 offset1:126
	global_load_dwordx4 v[102:105], v[72:73], off nt
	s_nop 0
	global_load_dwordx4 v[72:75], v[74:75], off nt
	v_add_u32_e32 v115, 0x101f8, v87
	v_lshl_add_u64 v[106:107], v[58:59], 0, v[46:47]
	v_lshl_add_u64 v[108:109], v[58:59], 0, v[2:3]
	v_add_u32_e32 v117, 0x102a0, v87
	ds_read_b32 v158, v115
	ds_read2_b32 v[160:161], v88 offset0:168 offset1:210
	ds_read_b32 v162, v117
	ds_read2_b32 v[164:165], v89 offset0:168 offset1:210
	ds_read2_b32 v[166:167], v90 offset0:168 offset1:210
	ds_read2_b32 v[168:169], v91 offset0:168 offset1:210
	ds_read2_b32 v[92:93], v92 offset0:168 offset1:210
	ds_read2_b32 v[170:171], v111 offset0:168 offset1:210
	ds_read2_b32 v[172:173], v113 offset0:168 offset1:210
	global_load_dwordx4 v[88:91], v[106:107], off nt
	s_nop 0
	global_load_dwordx4 v[106:109], v[108:109], off nt
	v_add_u32_e32 v119, 0x10348, v87
	s_waitcnt lgkmcnt(14)
	v_mov_b32_e32 v178, v61
	v_mov_b32_e32 v184, v127
	v_mov_b32_e32 v186, v129
	v_mov_b32_e32 v188, v131
	v_mov_b32_e32 v190, v133
	v_mov_b32_e32 v192, v135
	v_mov_b32_e32 v194, v137
	v_mov_b32_e32 v196, v139
	v_add_u32_e32 v121, 0x103f0, v87
	ds_read_b32 v174, v119
	ds_read_b32 v176, v121
	v_mov_b32_e32 v180, v65
	v_mov_b32_e32 v198, v145
	v_mov_b32_e32 v200, v147
	s_waitcnt lgkmcnt(14)
	v_mov_b32_e32 v202, v149
	v_mov_b32_e32 v206, v151
	s_waitcnt lgkmcnt(13)
	v_mov_b32_e32 v208, v153
	s_waitcnt lgkmcnt(12)
	v_mov_b32_e32 v210, v155
	s_waitcnt lgkmcnt(11)
	v_mov_b32_e32 v212, v157
	v_add_u32_e32 v0, 0x126, v0
	v_mov_b32_e32 v182, v71
	s_waitcnt lgkmcnt(9)
	v_mov_b32_e32 v214, v161
	s_waitcnt lgkmcnt(7)
	v_mov_b32_e32 v216, v165
	s_waitcnt lgkmcnt(6)
	v_mov_b32_e32 v218, v167
	s_waitcnt lgkmcnt(5)
	v_mov_b32_e32 v220, v169
	s_waitcnt lgkmcnt(4)
	v_mov_b32_e32 v222, v93
	s_waitcnt lgkmcnt(3)
	v_mov_b32_e32 v224, v171
	s_waitcnt lgkmcnt(2)
	v_mov_b32_e32 v226, v173
	v_cmp_lt_i32_e64 s[12:13], s37, v0
	v_lshl_add_u64 v[58:59], v[58:59], 0, s[26:27]
	v_add_u32_e32 v87, 0x498, v87
	s_or_b64 s[34:35], s[12:13], s[34:35]
	s_waitcnt vmcnt(6)
	v_pk_fma_f32 v[12:13], v[94:95], v[62:63], v[12:13] op_sel_hi:[1,0,1]
	v_pk_fma_f32 v[14:15], v[96:97], v[62:63], v[14:15] op_sel_hi:[1,0,1]
	v_pk_fma_f32 v[36:37], v[94:95], v[60:61], v[36:37] op_sel_hi:[1,0,1]
	v_pk_fma_f32 v[38:39], v[96:97], v[60:61], v[38:39] op_sel_hi:[1,0,1]
	v_pk_fma_f32 v[32:33], v[94:95], v[126:127], v[32:33] op_sel_hi:[1,0,1]
	v_pk_fma_f32 v[34:35], v[96:97], v[126:127], v[34:35] op_sel_hi:[1,0,1]
	v_pk_fma_f32 v[28:29], v[94:95], v[128:129], v[28:29] op_sel_hi:[1,0,1]
	v_pk_fma_f32 v[30:31], v[96:97], v[128:129], v[30:31] op_sel_hi:[1,0,1]
	v_pk_fma_f32 v[24:25], v[94:95], v[130:131], v[24:25] op_sel_hi:[1,0,1]
	v_pk_fma_f32 v[26:27], v[96:97], v[130:131], v[26:27] op_sel_hi:[1,0,1]
	v_pk_fma_f32 v[20:21], v[94:95], v[132:133], v[20:21] op_sel_hi:[1,0,1]
	v_pk_fma_f32 v[22:23], v[96:97], v[132:133], v[22:23] op_sel_hi:[1,0,1]
	v_pk_fma_f32 v[16:17], v[94:95], v[134:135], v[16:17] op_sel_hi:[1,0,1]
	v_pk_fma_f32 v[18:19], v[96:97], v[134:135], v[18:19] op_sel_hi:[1,0,1]
	v_pk_fma_f32 v[8:9], v[94:95], v[136:137], v[8:9] op_sel_hi:[1,0,1]
	v_pk_fma_f32 v[10:11], v[96:97], v[136:137], v[10:11] op_sel_hi:[1,0,1]
	v_pk_fma_f32 v[4:5], v[94:95], v[138:139], v[4:5] op_sel_hi:[1,0,1]
	v_pk_fma_f32 v[6:7], v[96:97], v[138:139], v[6:7] op_sel_hi:[1,0,1]
	s_waitcnt vmcnt(5)
	v_pk_fma_f32 v[38:39], v[100:101], v[178:179], v[38:39] op_sel_hi:[1,0,1]
	v_pk_fma_f32 v[36:37], v[98:99], v[178:179], v[36:37] op_sel_hi:[1,0,1]
	v_pk_fma_f32 v[34:35], v[100:101], v[184:185], v[34:35] op_sel_hi:[1,0,1]
	v_pk_fma_f32 v[32:33], v[98:99], v[184:185], v[32:33] op_sel_hi:[1,0,1]
	v_pk_fma_f32 v[30:31], v[100:101], v[186:187], v[30:31] op_sel_hi:[1,0,1]
	v_pk_fma_f32 v[28:29], v[98:99], v[186:187], v[28:29] op_sel_hi:[1,0,1]
	v_pk_fma_f32 v[26:27], v[100:101], v[188:189], v[26:27] op_sel_hi:[1,0,1]
	v_pk_fma_f32 v[24:25], v[98:99], v[188:189], v[24:25] op_sel_hi:[1,0,1]
	v_pk_fma_f32 v[22:23], v[100:101], v[190:191], v[22:23] op_sel_hi:[1,0,1]
	v_pk_fma_f32 v[20:21], v[98:99], v[190:191], v[20:21] op_sel_hi:[1,0,1]
	v_pk_fma_f32 v[18:19], v[100:101], v[192:193], v[18:19] op_sel_hi:[1,0,1]
	v_pk_fma_f32 v[16:17], v[98:99], v[192:193], v[16:17] op_sel_hi:[1,0,1]
	v_pk_fma_f32 v[10:11], v[100:101], v[194:195], v[10:11] op_sel_hi:[1,0,1]
	v_pk_fma_f32 v[8:9], v[98:99], v[194:195], v[8:9] op_sel_hi:[1,0,1]
	v_pk_fma_f32 v[6:7], v[100:101], v[196:197], v[6:7] op_sel_hi:[1,0,1]
	v_pk_fma_f32 v[4:5], v[98:99], v[196:197], v[4:5] op_sel_hi:[1,0,1]
	v_pk_fma_f32 v[14:15], v[100:101], v[140:141], v[14:15] op_sel_hi:[1,0,1]
	v_pk_fma_f32 v[12:13], v[98:99], v[140:141], v[12:13] op_sel_hi:[1,0,1]
	s_waitcnt vmcnt(4)
	v_pk_fma_f32 v[14:15], v[68:69], v[142:143], v[14:15] op_sel_hi:[1,0,1]
	v_pk_fma_f32 v[12:13], v[66:67], v[142:143], v[12:13] op_sel_hi:[1,0,1]
	v_pk_fma_f32 v[38:39], v[68:69], v[64:65], v[38:39] op_sel_hi:[1,0,1]
	v_pk_fma_f32 v[36:37], v[66:67], v[64:65], v[36:37] op_sel_hi:[1,0,1]
	v_pk_fma_f32 v[34:35], v[68:69], v[144:145], v[34:35] op_sel_hi:[1,0,1]
	v_pk_fma_f32 v[32:33], v[66:67], v[144:145], v[32:33] op_sel_hi:[1,0,1]
	v_pk_fma_f32 v[30:31], v[68:69], v[146:147], v[30:31] op_sel_hi:[1,0,1]
	v_pk_fma_f32 v[28:29], v[66:67], v[146:147], v[28:29] op_sel_hi:[1,0,1]
	v_pk_fma_f32 v[26:27], v[68:69], v[148:149], v[26:27] op_sel_hi:[1,0,1]
	v_pk_fma_f32 v[24:25], v[66:67], v[148:149], v[24:25] op_sel_hi:[1,0,1]
	v_pk_fma_f32 v[22:23], v[68:69], v[150:151], v[22:23] op_sel_hi:[1,0,1]
	v_pk_fma_f32 v[20:21], v[66:67], v[150:151], v[20:21] op_sel_hi:[1,0,1]
	v_pk_fma_f32 v[18:19], v[68:69], v[152:153], v[18:19] op_sel_hi:[1,0,1]
	v_pk_fma_f32 v[16:17], v[66:67], v[152:153], v[16:17] op_sel_hi:[1,0,1]
	v_pk_fma_f32 v[10:11], v[68:69], v[154:155], v[10:11] op_sel_hi:[1,0,1]
	v_pk_fma_f32 v[8:9], v[66:67], v[154:155], v[8:9] op_sel_hi:[1,0,1]
	v_pk_fma_f32 v[6:7], v[68:69], v[156:157], v[6:7] op_sel_hi:[1,0,1]
	v_pk_fma_f32 v[4:5], v[66:67], v[156:157], v[4:5] op_sel_hi:[1,0,1]
	s_waitcnt vmcnt(3)
	v_pk_fma_f32 v[38:39], v[104:105], v[180:181], v[38:39] op_sel_hi:[1,0,1]
	v_pk_fma_f32 v[36:37], v[102:103], v[180:181], v[36:37] op_sel_hi:[1,0,1]
	v_pk_fma_f32 v[34:35], v[104:105], v[198:199], v[34:35] op_sel_hi:[1,0,1]
	v_pk_fma_f32 v[32:33], v[102:103], v[198:199], v[32:33] op_sel_hi:[1,0,1]
	v_pk_fma_f32 v[30:31], v[104:105], v[200:201], v[30:31] op_sel_hi:[1,0,1]
	v_pk_fma_f32 v[28:29], v[102:103], v[200:201], v[28:29] op_sel_hi:[1,0,1]
	v_pk_fma_f32 v[26:27], v[104:105], v[202:203], v[26:27] op_sel_hi:[1,0,1]
	v_pk_fma_f32 v[24:25], v[102:103], v[202:203], v[24:25] op_sel_hi:[1,0,1]
	v_pk_fma_f32 v[22:23], v[104:105], v[206:207], v[22:23] op_sel_hi:[1,0,1]
	v_pk_fma_f32 v[20:21], v[102:103], v[206:207], v[20:21] op_sel_hi:[1,0,1]
	v_pk_fma_f32 v[18:19], v[104:105], v[208:209], v[18:19] op_sel_hi:[1,0,1]
	v_pk_fma_f32 v[16:17], v[102:103], v[208:209], v[16:17] op_sel_hi:[1,0,1]
	v_pk_fma_f32 v[10:11], v[104:105], v[210:211], v[10:11] op_sel_hi:[1,0,1]
	v_pk_fma_f32 v[8:9], v[102:103], v[210:211], v[8:9] op_sel_hi:[1,0,1]
	v_pk_fma_f32 v[6:7], v[104:105], v[212:213], v[6:7] op_sel_hi:[1,0,1]
	v_pk_fma_f32 v[4:5], v[102:103], v[212:213], v[4:5] op_sel_hi:[1,0,1]
	v_pk_fma_f32 v[14:15], v[104:105], v[158:159], v[14:15] op_sel_hi:[1,0,1]
	v_pk_fma_f32 v[12:13], v[102:103], v[158:159], v[12:13] op_sel_hi:[1,0,1]
	s_waitcnt vmcnt(2)
	v_pk_fma_f32 v[14:15], v[74:75], v[162:163], v[14:15] op_sel_hi:[1,0,1]
	v_pk_fma_f32 v[12:13], v[72:73], v[162:163], v[12:13] op_sel_hi:[1,0,1]
	v_pk_fma_f32 v[38:39], v[74:75], v[70:71], v[38:39] op_sel_hi:[1,0,1]
	v_pk_fma_f32 v[36:37], v[72:73], v[70:71], v[36:37] op_sel_hi:[1,0,1]
	v_pk_fma_f32 v[34:35], v[74:75], v[160:161], v[34:35] op_sel_hi:[1,0,1]
	v_pk_fma_f32 v[32:33], v[72:73], v[160:161], v[32:33] op_sel_hi:[1,0,1]
	v_pk_fma_f32 v[30:31], v[74:75], v[164:165], v[30:31] op_sel_hi:[1,0,1]
	v_pk_fma_f32 v[28:29], v[72:73], v[164:165], v[28:29] op_sel_hi:[1,0,1]
	v_pk_fma_f32 v[26:27], v[74:75], v[166:167], v[26:27] op_sel_hi:[1,0,1]
	v_pk_fma_f32 v[24:25], v[72:73], v[166:167], v[24:25] op_sel_hi:[1,0,1]
	v_pk_fma_f32 v[22:23], v[74:75], v[168:169], v[22:23] op_sel_hi:[1,0,1]
	v_pk_fma_f32 v[20:21], v[72:73], v[168:169], v[20:21] op_sel_hi:[1,0,1]
	v_pk_fma_f32 v[18:19], v[74:75], v[92:93], v[18:19] op_sel_hi:[1,0,1]
	v_pk_fma_f32 v[16:17], v[72:73], v[92:93], v[16:17] op_sel_hi:[1,0,1]
	v_pk_fma_f32 v[10:11], v[74:75], v[170:171], v[10:11] op_sel_hi:[1,0,1]
	v_pk_fma_f32 v[8:9], v[72:73], v[170:171], v[8:9] op_sel_hi:[1,0,1]
	v_pk_fma_f32 v[6:7], v[74:75], v[172:173], v[6:7] op_sel_hi:[1,0,1]
	v_pk_fma_f32 v[4:5], v[72:73], v[172:173], v[4:5] op_sel_hi:[1,0,1]
	s_waitcnt vmcnt(1)
	v_pk_fma_f32 v[38:39], v[90:91], v[182:183], v[38:39] op_sel_hi:[1,0,1]
	v_pk_fma_f32 v[36:37], v[88:89], v[182:183], v[36:37] op_sel_hi:[1,0,1]
	v_pk_fma_f32 v[34:35], v[90:91], v[214:215], v[34:35] op_sel_hi:[1,0,1]
	v_pk_fma_f32 v[32:33], v[88:89], v[214:215], v[32:33] op_sel_hi:[1,0,1]
	v_pk_fma_f32 v[30:31], v[90:91], v[216:217], v[30:31] op_sel_hi:[1,0,1]
	v_pk_fma_f32 v[28:29], v[88:89], v[216:217], v[28:29] op_sel_hi:[1,0,1]
	v_pk_fma_f32 v[26:27], v[90:91], v[218:219], v[26:27] op_sel_hi:[1,0,1]
	v_pk_fma_f32 v[24:25], v[88:89], v[218:219], v[24:25] op_sel_hi:[1,0,1]
	v_pk_fma_f32 v[22:23], v[90:91], v[220:221], v[22:23] op_sel_hi:[1,0,1]
	v_pk_fma_f32 v[20:21], v[88:89], v[220:221], v[20:21] op_sel_hi:[1,0,1]
	v_pk_fma_f32 v[18:19], v[90:91], v[222:223], v[18:19] op_sel_hi:[1,0,1]
	v_pk_fma_f32 v[16:17], v[88:89], v[222:223], v[16:17] op_sel_hi:[1,0,1]
	v_pk_fma_f32 v[10:11], v[90:91], v[224:225], v[10:11] op_sel_hi:[1,0,1]
	v_pk_fma_f32 v[8:9], v[88:89], v[224:225], v[8:9] op_sel_hi:[1,0,1]
	v_pk_fma_f32 v[6:7], v[90:91], v[226:227], v[6:7] op_sel_hi:[1,0,1]
	v_pk_fma_f32 v[4:5], v[88:89], v[226:227], v[4:5] op_sel_hi:[1,0,1]
	s_waitcnt lgkmcnt(1)
	v_pk_fma_f32 v[14:15], v[90:91], v[174:175], v[14:15] op_sel_hi:[1,0,1]
	v_pk_fma_f32 v[12:13], v[88:89], v[174:175], v[12:13] op_sel_hi:[1,0,1]
	s_waitcnt vmcnt(0)
	v_pk_fma_f32 v[38:39], v[108:109], v[112:113], v[38:39] op_sel_hi:[1,0,1]
	v_pk_fma_f32 v[36:37], v[106:107], v[112:113], v[36:37] op_sel_hi:[1,0,1]
	v_pk_fma_f32 v[34:35], v[108:109], v[114:115], v[34:35] op_sel_hi:[1,0,1]
	v_pk_fma_f32 v[32:33], v[106:107], v[114:115], v[32:33] op_sel_hi:[1,0,1]
	v_pk_fma_f32 v[30:31], v[108:109], v[116:117], v[30:31] op_sel_hi:[1,0,1]
	v_pk_fma_f32 v[28:29], v[106:107], v[116:117], v[28:29] op_sel_hi:[1,0,1]
	v_pk_fma_f32 v[26:27], v[108:109], v[110:111], v[26:27] op_sel_hi:[1,0,1]
	v_pk_fma_f32 v[24:25], v[106:107], v[110:111], v[24:25] op_sel_hi:[1,0,1]
	v_pk_fma_f32 v[22:23], v[108:109], v[118:119], v[22:23] op_sel_hi:[1,0,1]
	v_pk_fma_f32 v[20:21], v[106:107], v[118:119], v[20:21] op_sel_hi:[1,0,1]
	v_pk_fma_f32 v[18:19], v[108:109], v[120:121], v[18:19] op_sel_hi:[1,0,1]
	v_pk_fma_f32 v[16:17], v[106:107], v[120:121], v[16:17] op_sel_hi:[1,0,1]
	v_pk_fma_f32 v[10:11], v[108:109], v[124:125], v[10:11] op_sel_hi:[1,0,1]
	v_pk_fma_f32 v[8:9], v[106:107], v[124:125], v[8:9] op_sel_hi:[1,0,1]
	v_pk_fma_f32 v[6:7], v[108:109], v[122:123], v[6:7] op_sel_hi:[1,0,1]
	v_pk_fma_f32 v[4:5], v[106:107], v[122:123], v[4:5] op_sel_hi:[1,0,1]
	s_waitcnt lgkmcnt(0)
	v_pk_fma_f32 v[14:15], v[108:109], v[176:177], v[14:15] op_sel_hi:[1,0,1]
	v_pk_fma_f32 v[12:13], v[106:107], v[176:177], v[12:13] op_sel_hi:[1,0,1]
	s_andn2_b64 exec, exec, s[34:35]
	s_cbranch_execnz .LBB0_51
	s_or_b64 exec, exec, s[34:35]

.LBB0_88:
	v_mov_b32_e32 v39, 0
	v_lshlrev_b32_e32 v2, 2, v40
	v_and_b32_e32 v2, 60, v2
	v_mov_b32_e32 v8, v39
	v_mov_b32_e32 v9, v39
	v_ashrrev_i32_e32 v45, 6, v40
	v_cmp_lt_i32_e32 vcc, -1, v38
	s_waitcnt lgkmcnt(0)
	v_lshl_add_u64 v[0:1], v[38:39], 2, s[8:9]
	v_lshlrev_b32_e32 v38, 2, v2
	v_mov_b32_e32 v6, v39
	v_mov_b32_e32 v7, v39
	v_mov_b64_e32 v[12:13], v[8:9]
	v_and_b32_e32 v41, 63, v40
	v_add_u32_e32 v42, s4, v45
	v_lshl_add_u64 v[4:5], v[0:1], 0, v[38:39]
	v_mov_b64_e32 v[10:11], v[6:7]
	s_and_saveexec_b64 s[8:9], vcc
	s_cbranch_execz .LBB0_90
	v_ashrrev_i32_e32 v0, 31, v42
	v_mul_lo_u32 v2, s11, v42
	v_mul_lo_u32 v3, s10, v0
	v_mad_u64_u32 v[0:1], s[0:1], s10, v42, 0
	v_add3_u32 v1, v1, v3, v2
	v_lshl_add_u64 v[0:1], v[0:1], 2, v[4:5]
	global_load_dwordx4 v[10:13], v[0:1], off nt
.LBB0_90:
	s_or_b64 exec, exec, s[8:9]
	s_and_saveexec_b64 s[8:9], vcc
	s_cbranch_execz .LBB0_92
	v_add_u32_e32 v0, 8, v42
	v_ashrrev_i32_e32 v1, 31, v0
	v_mul_lo_u32 v2, s10, v1
	v_mul_lo_u32 v3, s11, v0
	v_mad_u64_u32 v[0:1], s[0:1], s10, v0, 0
	v_add3_u32 v1, v1, v2, v3
	v_lshl_add_u64 v[0:1], v[0:1], 2, v[4:5]
	global_load_dwordx4 v[6:9], v[0:1], off nt
.LBB0_92:
	s_or_b64 exec, exec, s[8:9]
	v_mov_b32_e32 v18, 0
	v_mov_b32_e32 v19, v18
	v_mov_b32_e32 v20, v18
	v_mov_b32_e32 v21, v18
	v_mov_b64_e32 v[14:15], v[18:19]
	v_mov_b64_e32 v[16:17], v[20:21]
	s_and_saveexec_b64 s[8:9], vcc
	s_cbranch_execz .LBB0_94
	v_add_u32_e32 v0, 16, v42
	v_ashrrev_i32_e32 v1, 31, v0
	v_mul_lo_u32 v2, s10, v1
	v_mul_lo_u32 v3, s11, v0
	v_mad_u64_u32 v[0:1], s[0:1], s10, v0, 0
	v_add3_u32 v1, v1, v2, v3
	v_lshl_add_u64 v[0:1], v[0:1], 2, v[4:5]
	global_load_dwordx4 v[14:17], v[0:1], off nt
.LBB0_94:
	s_or_b64 exec, exec, s[8:9]
	s_and_saveexec_b64 s[8:9], vcc
	s_cbranch_execz .LBB0_96
	v_add_u32_e32 v0, 24, v42
	v_ashrrev_i32_e32 v1, 31, v0
	v_mul_lo_u32 v2, s10, v1
	v_mul_lo_u32 v3, s11, v0
	v_mad_u64_u32 v[0:1], s[0:1], s10, v0, 0
	v_add3_u32 v1, v1, v2, v3
	v_lshl_add_u64 v[0:1], v[0:1], 2, v[4:5]
	global_load_dwordx4 v[18:21], v[0:1], off nt
.LBB0_96:
	s_or_b64 exec, exec, s[8:9]
	v_mov_b32_e32 v26, 0
	v_mov_b32_e32 v27, v26
	v_mov_b32_e32 v28, v26
	v_mov_b32_e32 v29, v26
	v_mov_b64_e32 v[22:23], v[26:27]
	v_mov_b64_e32 v[24:25], v[28:29]
	s_and_saveexec_b64 s[8:9], vcc
	s_cbranch_execz .LBB0_98
	v_add_u32_e32 v0, 32, v42
	v_ashrrev_i32_e32 v1, 31, v0
	v_mul_lo_u32 v2, s10, v1
	v_mul_lo_u32 v3, s11, v0
	v_mad_u64_u32 v[0:1], s[0:1], s10, v0, 0
	v_add3_u32 v1, v1, v2, v3
	v_lshl_add_u64 v[0:1], v[0:1], 2, v[4:5]
	global_load_dwordx4 v[22:25], v[0:1], off nt
.LBB0_98:
	s_or_b64 exec, exec, s[8:9]
	s_and_saveexec_b64 s[8:9], vcc
	s_cbranch_execz .LBB0_100
	v_add_u32_e32 v0, 40, v42
	v_ashrrev_i32_e32 v1, 31, v0
	v_mul_lo_u32 v2, s10, v1
	v_mul_lo_u32 v3, s11, v0
	v_mad_u64_u32 v[0:1], s[0:1], s10, v0, 0
	v_add3_u32 v1, v1, v2, v3
	v_lshl_add_u64 v[0:1], v[0:1], 2, v[4:5]
	global_load_dwordx4 v[26:29], v[0:1], off nt
.LBB0_100:
	s_or_b64 exec, exec, s[8:9]
	v_mov_b32_e32 v1, 0
	v_mov_b32_e32 v2, v1
	v_mov_b32_e32 v3, v1
	v_mov_b32_e32 v0, v1
	v_mov_b64_e32 v[32:33], v[2:3]
	v_mov_b64_e32 v[30:31], v[0:1]
	s_and_saveexec_b64 s[8:9], vcc
	s_cbranch_execz .LBB0_102
	v_add_u32_e32 v0, 48, v42
	v_ashrrev_i32_e32 v2, 31, v0
	v_mul_lo_u32 v30, s10, v2
	v_mul_lo_u32 v31, s11, v0
	v_mad_u64_u32 v[2:3], s[0:1], s10, v0, 0
	v_add3_u32 v3, v3, v30, v31
	v_lshl_add_u64 v[2:3], v[2:3], 2, v[4:5]
	global_load_dwordx4 v[30:33], v[2:3], off nt
.LBB0_102:
	s_or_b64 exec, exec, s[8:9]
	v_mov_b32_e32 v34, 0
	v_mov_b32_e32 v35, 0
	v_mov_b32_e32 v36, 0
	v_mov_b32_e32 v37, 0
	s_and_saveexec_b64 s[8:9], vcc
	s_cbranch_execz .LBB0_104
	v_add_u32_e32 v0, 56, v42
	v_ashrrev_i32_e32 v2, 31, v0
	v_mul_lo_u32 v34, s10, v2
	v_mul_lo_u32 v35, s11, v0
	v_mad_u64_u32 v[2:3], s[0:1], s10, v0, 0
	v_add3_u32 v3, v3, v34, v35
	v_lshl_add_u64 v[2:3], v[2:3], 2, v[4:5]
	global_load_dwordx4 v[34:37], v[2:3], off nt

.LBB0_135:
	v_mov_b32_e32 v8, v2
	v_mov_b32_e32 v9, v2
	s_waitcnt lgkmcnt(0)
	v_lshl_add_u64 v[4:5], v[0:1], 2, s[22:23]
	v_mov_b32_e32 v39, v1
	v_mov_b32_e32 v6, v2
	v_mov_b32_e32 v7, v2
	v_mov_b64_e32 v[12:13], v[8:9]
	v_cmp_lt_i32_e32 vcc, -1, v0
	v_add_u32_e32 v41, s44, v45
	v_lshl_add_u64 v[42:43], v[4:5], 0, v[38:39]
	v_mov_b64_e32 v[10:11], v[6:7]
	s_and_saveexec_b64 s[22:23], vcc
	s_cbranch_execz .LBB0_137
	v_ashrrev_i32_e32 v0, 31, v41
	v_mul_lo_u32 v3, s21, v41
	v_mul_lo_u32 v0, s20, v0
	v_mad_u64_u32 v[4:5], s[0:1], s20, v41, 0
	v_add3_u32 v5, v5, v0, v3
	v_lshl_add_u64 v[4:5], v[4:5], 2, v[42:43]
	global_load_dwordx4 v[10:13], v[4:5], off nt
.LBB0_137:
	s_or_b64 exec, exec, s[22:23]
	s_and_saveexec_b64 s[22:23], vcc
	s_cbranch_execz .LBB0_139
	v_add_u32_e32 v0, 8, v41
	v_ashrrev_i32_e32 v3, 31, v0
	v_mul_lo_u32 v3, s20, v3
	v_mul_lo_u32 v6, s21, v0
	v_mad_u64_u32 v[4:5], s[0:1], s20, v0, 0
	v_add3_u32 v5, v5, v3, v6
	v_lshl_add_u64 v[4:5], v[4:5], 2, v[42:43]
	global_load_dwordx4 v[6:9], v[4:5], off nt
.LBB0_139:
	s_or_b64 exec, exec, s[22:23]
	v_mov_b32_e32 v4, v2
	v_mov_b32_e32 v5, v2
	v_mov_b32_e32 v3, v2
	v_mov_b64_e32 v[16:17], v[4:5]
	v_mov_b64_e32 v[14:15], v[2:3]
	s_and_saveexec_b64 s[22:23], vcc
	s_cbranch_execz .LBB0_141
	v_add_u32_e32 v0, 16, v41
	v_ashrrev_i32_e32 v14, 31, v0
	v_mul_lo_u32 v16, s20, v14
	v_mul_lo_u32 v17, s21, v0
	v_mad_u64_u32 v[14:15], s[0:1], s20, v0, 0
	v_add3_u32 v15, v15, v16, v17
	v_lshl_add_u64 v[14:15], v[14:15], 2, v[42:43]
	global_load_dwordx4 v[14:17], v[14:15], off nt
.LBB0_141:
	s_or_b64 exec, exec, s[22:23]
	v_mov_b64_e32 v[20:21], v[4:5]
	v_mov_b64_e32 v[18:19], v[2:3]
	s_and_saveexec_b64 s[22:23], vcc
	s_cbranch_execz .LBB0_143
	v_add_u32_e32 v0, 24, v41
	v_ashrrev_i32_e32 v3, 31, v0
	v_mul_lo_u32 v3, s20, v3
	v_mul_lo_u32 v18, s21, v0
	v_mad_u64_u32 v[4:5], s[0:1], s20, v0, 0
	v_add3_u32 v5, v5, v3, v18
	v_lshl_add_u64 v[4:5], v[4:5], 2, v[42:43]
	global_load_dwordx4 v[18:21], v[4:5], off nt
.LBB0_143:
	s_or_b64 exec, exec, s[22:23]
	v_mov_b32_e32 v4, v2
	v_mov_b32_e32 v5, v2
	v_mov_b32_e32 v3, v2
	v_mov_b64_e32 v[24:25], v[4:5]
	v_mov_b64_e32 v[22:23], v[2:3]
	s_and_saveexec_b64 s[22:23], vcc
	s_cbranch_execz .LBB0_145
	v_add_u32_e32 v0, 32, v41
	v_ashrrev_i32_e32 v22, 31, v0
	v_mul_lo_u32 v24, s20, v22
	v_mul_lo_u32 v25, s21, v0
	v_mad_u64_u32 v[22:23], s[0:1], s20, v0, 0
	v_add3_u32 v23, v23, v24, v25
	v_lshl_add_u64 v[22:23], v[22:23], 2, v[42:43]
	global_load_dwordx4 v[22:25], v[22:23], off nt
.LBB0_145:
	s_or_b64 exec, exec, s[22:23]
	v_mov_b64_e32 v[28:29], v[4:5]
	v_mov_b64_e32 v[26:27], v[2:3]
	s_and_saveexec_b64 s[22:23], vcc
	s_cbranch_execz .LBB0_147
	v_add_u32_e32 v0, 40, v41
	v_ashrrev_i32_e32 v3, 31, v0
	v_mul_lo_u32 v3, s20, v3
	v_mul_lo_u32 v26, s21, v0
	v_mad_u64_u32 v[4:5], s[0:1], s20, v0, 0
	v_add3_u32 v5, v5, v3, v26
	v_lshl_add_u64 v[4:5], v[4:5], 2, v[42:43]
	global_load_dwordx4 v[26:29], v[4:5], off nt
.LBB0_147:
	s_or_b64 exec, exec, s[22:23]
	v_mov_b32_e32 v4, v2
	v_mov_b32_e32 v5, v2
	v_mov_b32_e32 v3, v2
	v_mov_b64_e32 v[32:33], v[4:5]
	v_mov_b64_e32 v[30:31], v[2:3]
	s_and_saveexec_b64 s[22:23], vcc
	s_cbranch_execz .LBB0_149
	v_add_u32_e32 v0, 48, v41
	v_ashrrev_i32_e32 v3, 31, v0
	v_mul_lo_u32 v3, s20, v3
	v_mul_lo_u32 v30, s21, v0
	v_mad_u64_u32 v[4:5], s[0:1], s20, v0, 0
	v_add3_u32 v5, v5, v3, v30
	v_lshl_add_u64 v[4:5], v[4:5], 2, v[42:43]
	global_load_dwordx4 v[30:33], v[4:5], off nt
.LBB0_149:
	s_or_b64 exec, exec, s[22:23]
	v_mov_b32_e32 v37, 0
	v_mov_b32_e32 v36, 0
	v_mov_b32_e32 v35, 0
	v_mov_b32_e32 v34, 0
	s_and_saveexec_b64 s[22:23], vcc
	s_cbranch_execz .LBB0_105
	v_add_u32_e32 v0, 56, v41
	v_ashrrev_i32_e32 v3, 31, v0
	v_mul_lo_u32 v3, s20, v3
	v_mul_lo_u32 v34, s21, v0
	v_mad_u64_u32 v[4:5], s[0:1], s20, v0, 0
	v_add3_u32 v5, v5, v3, v34
	v_lshl_add_u64 v[4:5], v[4:5], 2, v[42:43]
	global_load_dwordx4 v[34:37], v[4:5], off nt
	s_branch .LBB0_105

.LBB0_1386:
	s_load_dwordx2 s[0:1], s[4:5], 0x0
	v_lshlrev_b32_e32 v2, 2, v8
	v_and_b32_e32 v41, 0xc0, v2
	v_or_b32_e32 v36, s26, v41
	v_mov_b32_e32 v37, 0
	v_and_b32_e32 v2, 60, v2
	v_ashrrev_i32_e32 v40, 6, v8
	s_cmp_gt_i32 s26, -1
	s_waitcnt lgkmcnt(0)
	v_lshl_add_u64 v[0:1], v[36:37], 2, s[0:1]
	v_lshlrev_b32_e32 v36, 2, v2
	s_cselect_b64 s[12:13], -1, 0
	s_cmp_lt_i32 s26, 0
	v_add_u32_e32 v38, s6, v40
	v_lshl_add_u64 v[10:11], v[0:1], 0, v[36:37]
	s_cbranch_scc1 .LBB0_1394
	v_mad_i64_i32 v[0:1], s[0:1], s10, v38, 0
	v_lshl_add_u64 v[0:1], v[0:1], 2, v[10:11]
	global_load_dwordx4 v[0:3], v[0:1], off nt
	v_cndmask_b32_e64 v4, 0, 1, s[12:13]
	v_cmp_ne_u32_e64 s[4:5], 1, v4
	s_andn2_b64 vcc, exec, s[12:13]
	s_cbranch_vccnz .LBB0_1395
.LBB0_1388:
	v_add_u32_e32 v4, 8, v38
	v_mad_i64_i32 v[4:5], s[0:1], s10, v4, 0
	v_lshl_add_u64 v[4:5], v[4:5], 2, v[10:11]
	global_load_dwordx4 v[4:7], v[4:5], off nt
	s_and_b64 vcc, exec, s[4:5]
	s_cbranch_vccnz .LBB0_1396
.LBB0_1389:
	v_add_u32_e32 v9, 16, v38
	v_mad_i64_i32 v[12:13], s[0:1], s10, v9, 0
	v_lshl_add_u64 v[12:13], v[12:13], 2, v[10:11]
	global_load_dwordx4 v[12:15], v[12:13], off nt
	s_and_b64 vcc, exec, s[4:5]
	s_cbranch_vccnz .LBB0_1397
.LBB0_1390:
	v_add_u32_e32 v9, 24, v38
	v_mad_i64_i32 v[16:17], s[0:1], s10, v9, 0
	v_lshl_add_u64 v[16:17], v[16:17], 2, v[10:11]
	global_load_dwordx4 v[16:19], v[16:17], off nt
	s_and_b64 vcc, exec, s[4:5]
	s_cbranch_vccnz .LBB0_1398
.LBB0_1391:
	v_add_u32_e32 v9, 32, v38
	v_mad_i64_i32 v[20:21], s[0:1], s10, v9, 0
	v_lshl_add_u64 v[20:21], v[20:21], 2, v[10:11]
	global_load_dwordx4 v[20:23], v[20:21], off nt
	s_and_b64 vcc, exec, s[4:5]
	s_cbranch_vccnz .LBB0_1399
.LBB0_1392:
	v_add_u32_e32 v9, 40, v38
	v_mad_i64_i32 v[24:25], s[0:1], s10, v9, 0
	v_lshl_add_u64 v[24:25], v[24:25], 2, v[10:11]
	global_load_dwordx4 v[24:27], v[24:25], off nt
	s_and_b64 vcc, exec, s[4:5]
	s_cbranch_vccnz .LBB0_1400
.LBB0_1393:
	v_add_u32_e32 v9, 48, v38
	v_mad_i64_i32 v[28:29], s[0:1], s10, v9, 0
	v_lshl_add_u64 v[28:29], v[28:29], 2, v[10:11]
	global_load_dwordx4 v[28:31], v[28:29], off nt
	s_branch .LBB0_1401

.LBB0_1401:
	v_and_b32_e32 v37, 63, v8
	v_mov_b32_e32 v9, 0
	s_and_b64 vcc, exec, s[4:5]
	v_mov_b32_e32 v32, 0
	v_mov_b32_e32 v33, 0
	v_mov_b32_e32 v34, 0
	v_mov_b32_e32 v35, 0
	s_cbranch_vccnz .LBB0_1403
	v_add_u32_e32 v32, 56, v38
	v_mad_i64_i32 v[32:33], s[0:1], s10, v32, 0
	v_lshl_add_u64 v[10:11], v[32:33], 2, v[10:11]
	global_load_dwordx4 v[32:35], v[10:11], off nt

.LBB0_1404:
	v_add_u32_e32 v8, 56, v34
	v_mad_i64_i32 v[10:11], s[0:1], s22, v8, 0
	v_lshl_add_u64 v[10:11], v[10:11], 2, v[32:33]
	global_load_dwordx4 v[32:35], v[10:11], off nt

.LBB0_1412:
	s_load_dwordx2 s[0:1], s[4:5], 0x0
	v_or_b32_e32 v8, s34, v41
	s_cmp_gt_i32 s34, -1
	v_mov_b32_e32 v37, v9
	s_cselect_b64 s[24:25], -1, 0
	s_waitcnt lgkmcnt(0)
	v_lshl_add_u64 v[0:1], v[8:9], 2, s[0:1]
	s_cmp_lt_i32 s34, 0
	v_add_u32_e32 v34, s36, v40
	v_lshl_add_u64 v[32:33], v[0:1], 0, v[36:37]
	s_cbranch_scc1 .LBB0_1420
	v_mad_i64_i32 v[0:1], s[0:1], s22, v34, 0
	v_lshl_add_u64 v[0:1], v[0:1], 2, v[32:33]
	global_load_dwordx4 v[0:3], v[0:1], off nt
	v_cndmask_b32_e64 v4, 0, 1, s[24:25]
	v_cmp_ne_u32_e64 s[4:5], 1, v4
	s_andn2_b64 vcc, exec, s[24:25]
	s_cbranch_vccnz .LBB0_1421
.LBB0_1414:
	v_add_u32_e32 v4, 8, v34
	v_mad_i64_i32 v[4:5], s[0:1], s22, v4, 0
	v_lshl_add_u64 v[4:5], v[4:5], 2, v[32:33]
	global_load_dwordx4 v[4:7], v[4:5], off nt
	s_and_b64 vcc, exec, s[4:5]
	s_cbranch_vccnz .LBB0_1422
.LBB0_1415:
	v_add_u32_e32 v8, 16, v34
	v_mad_i64_i32 v[10:11], s[0:1], s22, v8, 0
	v_lshl_add_u64 v[10:11], v[10:11], 2, v[32:33]
	global_load_dwordx4 v[12:15], v[10:11], off nt
	s_and_b64 vcc, exec, s[4:5]
	s_cbranch_vccnz .LBB0_1423
.LBB0_1416:
	v_add_u32_e32 v8, 24, v34
	v_mad_i64_i32 v[10:11], s[0:1], s22, v8, 0
	v_lshl_add_u64 v[10:11], v[10:11], 2, v[32:33]
	global_load_dwordx4 v[16:19], v[10:11], off nt
	s_and_b64 vcc, exec, s[4:5]
	s_cbranch_vccnz .LBB0_1424
.LBB0_1417:
	v_add_u32_e32 v8, 32, v34
	v_mad_i64_i32 v[10:11], s[0:1], s22, v8, 0
	v_lshl_add_u64 v[10:11], v[10:11], 2, v[32:33]
	global_load_dwordx4 v[20:23], v[10:11], off nt
	s_and_b64 vcc, exec, s[4:5]
	s_cbranch_vccnz .LBB0_1425
.LBB0_1418:
	v_add_u32_e32 v8, 40, v34
	v_mad_i64_i32 v[10:11], s[0:1], s22, v8, 0
	v_lshl_add_u64 v[10:11], v[10:11], 2, v[32:33]
	global_load_dwordx4 v[24:27], v[10:11], off nt
	s_and_b64 vcc, exec, s[4:5]
	s_cbranch_vccnz .LBB0_1426
.LBB0_1419:
	v_add_u32_e32 v8, 48, v34
	v_mad_i64_i32 v[10:11], s[0:1], s22, v8, 0
	v_lshl_add_u64 v[10:11], v[10:11], 2, v[32:33]
	global_load_dwordx4 v[28:31], v[10:11], off nt
	s_and_b64 vcc, exec, s[4:5]
	s_cbranch_vccz .LBB0_1404
	s_branch .LBB0_1427
